# P6 epilogue stores rewritten to full 128B lines via even/odd lane DPP exchange
# speedup vs baseline: 1.0131x; 1.0131x over previous
.LBB0_485:
	v_lshl_add_u32 v150, s36, 8, v140
	v_lshl_or_b32 v152, s77, 8, v143
	v_and_b32_e32 v156, 1, v150
	v_and_b32_e32 v150, -2, v150
	v_lshl_add_u32 v152, v156, 4, v152
	s_mov_b32 s101, 0
	s_mov_b32 vcc_lo, 0x55555555
	s_mov_b32 vcc_hi, 0x55555555
	v_ashrrev_i32_e32 v151, 31, v150
	v_ashrrev_i32_e32 v153, 31, v152
	v_lshlrev_b64 v[154:155], 13, v[150:151]
	v_lshl_add_u64 v[154:155], s[14:15], 0, v[154:155]
	v_lshlrev_b64 v[152:153], 2, v[152:153]
	v_lshl_add_u64 v[154:155], v[154:155], 0, v[152:153]
	s_mov_b32 s100, 0x0
	v_lshl_add_u64 v[158:159], v[154:155], 0, s[100:101]
	s_mov_b32 s100, 0x2000
	v_lshl_add_u64 v[160:161], v[154:155], 0, s[100:101]
	v_cndmask_b32_dpp v184, v4, v0, vcc quad_perm:[0,0,2,2] row_mask:0xf bank_mask:0xf
	v_cndmask_b32_dpp v185, v5, v1, vcc quad_perm:[0,0,2,2] row_mask:0xf bank_mask:0xf
	v_cndmask_b32_dpp v186, v6, v2, vcc quad_perm:[0,0,2,2] row_mask:0xf bank_mask:0xf
	v_cndmask_b32_dpp v187, v7, v3, vcc quad_perm:[0,0,2,2] row_mask:0xf bank_mask:0xf
	v_cndmask_b32_dpp v188, v20, v16, vcc quad_perm:[0,0,2,2] row_mask:0xf bank_mask:0xf
	v_cndmask_b32_dpp v189, v21, v17, vcc quad_perm:[0,0,2,2] row_mask:0xf bank_mask:0xf
	v_cndmask_b32_dpp v190, v22, v18, vcc quad_perm:[0,0,2,2] row_mask:0xf bank_mask:0xf
	v_cndmask_b32_dpp v191, v23, v19, vcc quad_perm:[0,0,2,2] row_mask:0xf bank_mask:0xf
	s_not_b64 vcc, vcc
	v_cndmask_b32_dpp v4, v0, v4, vcc quad_perm:[1,1,3,3] row_mask:0xf bank_mask:0xf
	v_cndmask_b32_dpp v5, v1, v5, vcc quad_perm:[1,1,3,3] row_mask:0xf bank_mask:0xf
	v_cndmask_b32_dpp v6, v2, v6, vcc quad_perm:[1,1,3,3] row_mask:0xf bank_mask:0xf
	v_cndmask_b32_dpp v7, v3, v7, vcc quad_perm:[1,1,3,3] row_mask:0xf bank_mask:0xf
	v_cndmask_b32_dpp v20, v16, v20, vcc quad_perm:[1,1,3,3] row_mask:0xf bank_mask:0xf
	v_cndmask_b32_dpp v21, v17, v21, vcc quad_perm:[1,1,3,3] row_mask:0xf bank_mask:0xf
	v_cndmask_b32_dpp v22, v18, v22, vcc quad_perm:[1,1,3,3] row_mask:0xf bank_mask:0xf
	v_cndmask_b32_dpp v23, v19, v23, vcc quad_perm:[1,1,3,3] row_mask:0xf bank_mask:0xf
	s_not_b64 vcc, vcc
	global_store_dwordx4 v[158:159], v[184:187], off nt
	global_store_dwordx4 v[158:159], v[188:191], off offset:512 nt
	global_store_dwordx4 v[160:161], v[4:7], off nt
	global_store_dwordx4 v[160:161], v[20:23], off offset:512 nt
	s_mov_b32 s100, 0x20000
	v_lshl_add_u64 v[158:159], v[154:155], 0, s[100:101]
	s_mov_b32 s100, 0x22000
	v_lshl_add_u64 v[160:161], v[154:155], 0, s[100:101]
	v_cndmask_b32_dpp v192, v12, v8, vcc quad_perm:[0,0,2,2] row_mask:0xf bank_mask:0xf
	v_cndmask_b32_dpp v193, v13, v9, vcc quad_perm:[0,0,2,2] row_mask:0xf bank_mask:0xf
	v_cndmask_b32_dpp v194, v14, v10, vcc quad_perm:[0,0,2,2] row_mask:0xf bank_mask:0xf
	v_cndmask_b32_dpp v195, v15, v11, vcc quad_perm:[0,0,2,2] row_mask:0xf bank_mask:0xf
	v_cndmask_b32_dpp v196, v36, v32, vcc quad_perm:[0,0,2,2] row_mask:0xf bank_mask:0xf
	v_cndmask_b32_dpp v197, v37, v33, vcc quad_perm:[0,0,2,2] row_mask:0xf bank_mask:0xf
	v_cndmask_b32_dpp v198, v38, v34, vcc quad_perm:[0,0,2,2] row_mask:0xf bank_mask:0xf
	v_cndmask_b32_dpp v199, v39, v35, vcc quad_perm:[0,0,2,2] row_mask:0xf bank_mask:0xf
	s_not_b64 vcc, vcc
	v_cndmask_b32_dpp v12, v8, v12, vcc quad_perm:[1,1,3,3] row_mask:0xf bank_mask:0xf
	v_cndmask_b32_dpp v13, v9, v13, vcc quad_perm:[1,1,3,3] row_mask:0xf bank_mask:0xf
	v_cndmask_b32_dpp v14, v10, v14, vcc quad_perm:[1,1,3,3] row_mask:0xf bank_mask:0xf
	v_cndmask_b32_dpp v15, v11, v15, vcc quad_perm:[1,1,3,3] row_mask:0xf bank_mask:0xf
	v_cndmask_b32_dpp v36, v32, v36, vcc quad_perm:[1,1,3,3] row_mask:0xf bank_mask:0xf
	v_cndmask_b32_dpp v37, v33, v37, vcc quad_perm:[1,1,3,3] row_mask:0xf bank_mask:0xf
	v_cndmask_b32_dpp v38, v34, v38, vcc quad_perm:[1,1,3,3] row_mask:0xf bank_mask:0xf
	v_cndmask_b32_dpp v39, v35, v39, vcc quad_perm:[1,1,3,3] row_mask:0xf bank_mask:0xf
	s_not_b64 vcc, vcc
	global_store_dwordx4 v[158:159], v[192:195], off nt
	global_store_dwordx4 v[158:159], v[196:199], off offset:512 nt
	global_store_dwordx4 v[160:161], v[12:15], off nt
	global_store_dwordx4 v[160:161], v[36:39], off offset:512 nt
	s_mov_b32 s100, 0x40000
	v_lshl_add_u64 v[158:159], v[154:155], 0, s[100:101]
	s_mov_b32 s100, 0x42000
	v_lshl_add_u64 v[160:161], v[154:155], 0, s[100:101]
	v_cndmask_b32_dpp v184, v28, v24, vcc quad_perm:[0,0,2,2] row_mask:0xf bank_mask:0xf
	v_cndmask_b32_dpp v185, v29, v25, vcc quad_perm:[0,0,2,2] row_mask:0xf bank_mask:0xf
	v_cndmask_b32_dpp v186, v30, v26, vcc quad_perm:[0,0,2,2] row_mask:0xf bank_mask:0xf
	v_cndmask_b32_dpp v187, v31, v27, vcc quad_perm:[0,0,2,2] row_mask:0xf bank_mask:0xf
	v_cndmask_b32_dpp v188, v52, v48, vcc quad_perm:[0,0,2,2] row_mask:0xf bank_mask:0xf
	v_cndmask_b32_dpp v189, v53, v49, vcc quad_perm:[0,0,2,2] row_mask:0xf bank_mask:0xf
	v_cndmask_b32_dpp v190, v54, v50, vcc quad_perm:[0,0,2,2] row_mask:0xf bank_mask:0xf
	v_cndmask_b32_dpp v191, v55, v51, vcc quad_perm:[0,0,2,2] row_mask:0xf bank_mask:0xf
	s_not_b64 vcc, vcc
	v_cndmask_b32_dpp v28, v24, v28, vcc quad_perm:[1,1,3,3] row_mask:0xf bank_mask:0xf
	v_cndmask_b32_dpp v29, v25, v29, vcc quad_perm:[1,1,3,3] row_mask:0xf bank_mask:0xf
	v_cndmask_b32_dpp v30, v26, v30, vcc quad_perm:[1,1,3,3] row_mask:0xf bank_mask:0xf
	v_cndmask_b32_dpp v31, v27, v31, vcc quad_perm:[1,1,3,3] row_mask:0xf bank_mask:0xf
	v_cndmask_b32_dpp v52, v48, v52, vcc quad_perm:[1,1,3,3] row_mask:0xf bank_mask:0xf
	v_cndmask_b32_dpp v53, v49, v53, vcc quad_perm:[1,1,3,3] row_mask:0xf bank_mask:0xf
	v_cndmask_b32_dpp v54, v50, v54, vcc quad_perm:[1,1,3,3] row_mask:0xf bank_mask:0xf
	v_cndmask_b32_dpp v55, v51, v55, vcc quad_perm:[1,1,3,3] row_mask:0xf bank_mask:0xf
	s_not_b64 vcc, vcc
	global_store_dwordx4 v[158:159], v[184:187], off nt
	global_store_dwordx4 v[158:159], v[188:191], off offset:512 nt
	global_store_dwordx4 v[160:161], v[28:31], off nt
	global_store_dwordx4 v[160:161], v[52:55], off offset:512 nt
	s_mov_b32 s100, 0x60000
	v_lshl_add_u64 v[158:159], v[154:155], 0, s[100:101]
	s_mov_b32 s100, 0x62000
	v_lshl_add_u64 v[160:161], v[154:155], 0, s[100:101]
	v_cndmask_b32_dpp v192, v44, v40, vcc quad_perm:[0,0,2,2] row_mask:0xf bank_mask:0xf
	v_cndmask_b32_dpp v193, v45, v41, vcc quad_perm:[0,0,2,2] row_mask:0xf bank_mask:0xf
	v_cndmask_b32_dpp v194, v46, v42, vcc quad_perm:[0,0,2,2] row_mask:0xf bank_mask:0xf
	v_cndmask_b32_dpp v195, v47, v43, vcc quad_perm:[0,0,2,2] row_mask:0xf bank_mask:0xf
	v_cndmask_b32_dpp v196, v60, v56, vcc quad_perm:[0,0,2,2] row_mask:0xf bank_mask:0xf
	v_cndmask_b32_dpp v197, v61, v57, vcc quad_perm:[0,0,2,2] row_mask:0xf bank_mask:0xf
	v_cndmask_b32_dpp v198, v62, v58, vcc quad_perm:[0,0,2,2] row_mask:0xf bank_mask:0xf
	v_cndmask_b32_dpp v199, v63, v59, vcc quad_perm:[0,0,2,2] row_mask:0xf bank_mask:0xf
	s_not_b64 vcc, vcc
	v_cndmask_b32_dpp v44, v40, v44, vcc quad_perm:[1,1,3,3] row_mask:0xf bank_mask:0xf
	v_cndmask_b32_dpp v45, v41, v45, vcc quad_perm:[1,1,3,3] row_mask:0xf bank_mask:0xf
	v_cndmask_b32_dpp v46, v42, v46, vcc quad_perm:[1,1,3,3] row_mask:0xf bank_mask:0xf
	v_cndmask_b32_dpp v47, v43, v47, vcc quad_perm:[1,1,3,3] row_mask:0xf bank_mask:0xf
	v_cndmask_b32_dpp v60, v56, v60, vcc quad_perm:[1,1,3,3] row_mask:0xf bank_mask:0xf
	v_cndmask_b32_dpp v61, v57, v61, vcc quad_perm:[1,1,3,3] row_mask:0xf bank_mask:0xf
	v_cndmask_b32_dpp v62, v58, v62, vcc quad_perm:[1,1,3,3] row_mask:0xf bank_mask:0xf
	v_cndmask_b32_dpp v63, v59, v63, vcc quad_perm:[1,1,3,3] row_mask:0xf bank_mask:0xf
	s_not_b64 vcc, vcc
	global_store_dwordx4 v[158:159], v[192:195], off nt
	global_store_dwordx4 v[158:159], v[196:199], off offset:512 nt
	global_store_dwordx4 v[160:161], v[44:47], off nt
	global_store_dwordx4 v[160:161], v[60:63], off offset:512 nt
	s_mov_b32 s100, 0x100000
	v_lshl_add_u64 v[158:159], v[154:155], 0, s[100:101]
	s_mov_b32 s100, 0x102000
	v_lshl_add_u64 v[160:161], v[154:155], 0, s[100:101]
	v_cndmask_b32_dpp v184, v68, v64, vcc quad_perm:[0,0,2,2] row_mask:0xf bank_mask:0xf
	v_cndmask_b32_dpp v185, v69, v65, vcc quad_perm:[0,0,2,2] row_mask:0xf bank_mask:0xf
	v_cndmask_b32_dpp v186, v70, v66, vcc quad_perm:[0,0,2,2] row_mask:0xf bank_mask:0xf
	v_cndmask_b32_dpp v187, v71, v67, vcc quad_perm:[0,0,2,2] row_mask:0xf bank_mask:0xf
	v_cndmask_b32_dpp v188, v84, v80, vcc quad_perm:[0,0,2,2] row_mask:0xf bank_mask:0xf
	v_cndmask_b32_dpp v189, v85, v81, vcc quad_perm:[0,0,2,2] row_mask:0xf bank_mask:0xf
	v_cndmask_b32_dpp v190, v86, v82, vcc quad_perm:[0,0,2,2] row_mask:0xf bank_mask:0xf
	v_cndmask_b32_dpp v191, v87, v83, vcc quad_perm:[0,0,2,2] row_mask:0xf bank_mask:0xf
	s_not_b64 vcc, vcc
	v_cndmask_b32_dpp v68, v64, v68, vcc quad_perm:[1,1,3,3] row_mask:0xf bank_mask:0xf
	v_cndmask_b32_dpp v69, v65, v69, vcc quad_perm:[1,1,3,3] row_mask:0xf bank_mask:0xf
	v_cndmask_b32_dpp v70, v66, v70, vcc quad_perm:[1,1,3,3] row_mask:0xf bank_mask:0xf
	v_cndmask_b32_dpp v71, v67, v71, vcc quad_perm:[1,1,3,3] row_mask:0xf bank_mask:0xf
	v_cndmask_b32_dpp v84, v80, v84, vcc quad_perm:[1,1,3,3] row_mask:0xf bank_mask:0xf
	v_cndmask_b32_dpp v85, v81, v85, vcc quad_perm:[1,1,3,3] row_mask:0xf bank_mask:0xf
	v_cndmask_b32_dpp v86, v82, v86, vcc quad_perm:[1,1,3,3] row_mask:0xf bank_mask:0xf
	v_cndmask_b32_dpp v87, v83, v87, vcc quad_perm:[1,1,3,3] row_mask:0xf bank_mask:0xf
	s_not_b64 vcc, vcc
	global_store_dwordx4 v[158:159], v[184:187], off nt
	global_store_dwordx4 v[158:159], v[188:191], off offset:512 nt
	global_store_dwordx4 v[160:161], v[68:71], off nt
	global_store_dwordx4 v[160:161], v[84:87], off offset:512 nt
	s_mov_b32 s100, 0x120000
	v_lshl_add_u64 v[158:159], v[154:155], 0, s[100:101]
	s_mov_b32 s100, 0x122000
	v_lshl_add_u64 v[160:161], v[154:155], 0, s[100:101]
	v_cndmask_b32_dpp v192, v76, v72, vcc quad_perm:[0,0,2,2] row_mask:0xf bank_mask:0xf
	v_cndmask_b32_dpp v193, v77, v73, vcc quad_perm:[0,0,2,2] row_mask:0xf bank_mask:0xf
	v_cndmask_b32_dpp v194, v78, v74, vcc quad_perm:[0,0,2,2] row_mask:0xf bank_mask:0xf
	v_cndmask_b32_dpp v195, v79, v75, vcc quad_perm:[0,0,2,2] row_mask:0xf bank_mask:0xf
	v_cndmask_b32_dpp v196, v96, v92, vcc quad_perm:[0,0,2,2] row_mask:0xf bank_mask:0xf
	v_cndmask_b32_dpp v197, v97, v93, vcc quad_perm:[0,0,2,2] row_mask:0xf bank_mask:0xf
	v_cndmask_b32_dpp v198, v98, v94, vcc quad_perm:[0,0,2,2] row_mask:0xf bank_mask:0xf
	v_cndmask_b32_dpp v199, v99, v95, vcc quad_perm:[0,0,2,2] row_mask:0xf bank_mask:0xf
	s_not_b64 vcc, vcc
	v_cndmask_b32_dpp v76, v72, v76, vcc quad_perm:[1,1,3,3] row_mask:0xf bank_mask:0xf
	v_cndmask_b32_dpp v77, v73, v77, vcc quad_perm:[1,1,3,3] row_mask:0xf bank_mask:0xf
	v_cndmask_b32_dpp v78, v74, v78, vcc quad_perm:[1,1,3,3] row_mask:0xf bank_mask:0xf
	v_cndmask_b32_dpp v79, v75, v79, vcc quad_perm:[1,1,3,3] row_mask:0xf bank_mask:0xf
	v_cndmask_b32_dpp v96, v92, v96, vcc quad_perm:[1,1,3,3] row_mask:0xf bank_mask:0xf
	v_cndmask_b32_dpp v97, v93, v97, vcc quad_perm:[1,1,3,3] row_mask:0xf bank_mask:0xf
	v_cndmask_b32_dpp v98, v94, v98, vcc quad_perm:[1,1,3,3] row_mask:0xf bank_mask:0xf
	v_cndmask_b32_dpp v99, v95, v99, vcc quad_perm:[1,1,3,3] row_mask:0xf bank_mask:0xf
	s_not_b64 vcc, vcc
	global_store_dwordx4 v[158:159], v[192:195], off nt
	global_store_dwordx4 v[158:159], v[196:199], off offset:512 nt
	global_store_dwordx4 v[160:161], v[76:79], off nt
	global_store_dwordx4 v[160:161], v[96:99], off offset:512 nt
	s_mov_b32 s100, 0x140000
	v_lshl_add_u64 v[158:159], v[154:155], 0, s[100:101]
	s_mov_b32 s100, 0x142000
	v_lshl_add_u64 v[160:161], v[154:155], 0, s[100:101]
	v_cndmask_b32_dpp v184, v100, v88, vcc quad_perm:[0,0,2,2] row_mask:0xf bank_mask:0xf
	v_cndmask_b32_dpp v185, v101, v89, vcc quad_perm:[0,0,2,2] row_mask:0xf bank_mask:0xf
	v_cndmask_b32_dpp v186, v102, v90, vcc quad_perm:[0,0,2,2] row_mask:0xf bank_mask:0xf
	v_cndmask_b32_dpp v187, v103, v91, vcc quad_perm:[0,0,2,2] row_mask:0xf bank_mask:0xf
	v_cndmask_b32_dpp v188, v116, v112, vcc quad_perm:[0,0,2,2] row_mask:0xf bank_mask:0xf
	v_cndmask_b32_dpp v189, v117, v113, vcc quad_perm:[0,0,2,2] row_mask:0xf bank_mask:0xf
	v_cndmask_b32_dpp v190, v118, v114, vcc quad_perm:[0,0,2,2] row_mask:0xf bank_mask:0xf
	v_cndmask_b32_dpp v191, v119, v115, vcc quad_perm:[0,0,2,2] row_mask:0xf bank_mask:0xf
	s_not_b64 vcc, vcc
	v_cndmask_b32_dpp v100, v88, v100, vcc quad_perm:[1,1,3,3] row_mask:0xf bank_mask:0xf
	v_cndmask_b32_dpp v101, v89, v101, vcc quad_perm:[1,1,3,3] row_mask:0xf bank_mask:0xf
	v_cndmask_b32_dpp v102, v90, v102, vcc quad_perm:[1,1,3,3] row_mask:0xf bank_mask:0xf
	v_cndmask_b32_dpp v103, v91, v103, vcc quad_perm:[1,1,3,3] row_mask:0xf bank_mask:0xf
	v_cndmask_b32_dpp v116, v112, v116, vcc quad_perm:[1,1,3,3] row_mask:0xf bank_mask:0xf
	v_cndmask_b32_dpp v117, v113, v117, vcc quad_perm:[1,1,3,3] row_mask:0xf bank_mask:0xf
	v_cndmask_b32_dpp v118, v114, v118, vcc quad_perm:[1,1,3,3] row_mask:0xf bank_mask:0xf
	v_cndmask_b32_dpp v119, v115, v119, vcc quad_perm:[1,1,3,3] row_mask:0xf bank_mask:0xf
	s_not_b64 vcc, vcc
	global_store_dwordx4 v[158:159], v[184:187], off nt
	global_store_dwordx4 v[158:159], v[188:191], off offset:512 nt
	global_store_dwordx4 v[160:161], v[100:103], off nt
	global_store_dwordx4 v[160:161], v[116:119], off offset:512 nt
	s_mov_b32 s100, 0x160000
	v_lshl_add_u64 v[158:159], v[154:155], 0, s[100:101]
	s_mov_b32 s100, 0x162000
	v_lshl_add_u64 v[160:161], v[154:155], 0, s[100:101]
	v_cndmask_b32_dpp v192, v108, v104, vcc quad_perm:[0,0,2,2] row_mask:0xf bank_mask:0xf
	v_cndmask_b32_dpp v193, v109, v105, vcc quad_perm:[0,0,2,2] row_mask:0xf bank_mask:0xf
	v_cndmask_b32_dpp v194, v110, v106, vcc quad_perm:[0,0,2,2] row_mask:0xf bank_mask:0xf
	v_cndmask_b32_dpp v195, v111, v107, vcc quad_perm:[0,0,2,2] row_mask:0xf bank_mask:0xf
	v_cndmask_b32_dpp v196, v124, v120, vcc quad_perm:[0,0,2,2] row_mask:0xf bank_mask:0xf
	v_cndmask_b32_dpp v197, v125, v121, vcc quad_perm:[0,0,2,2] row_mask:0xf bank_mask:0xf
	v_cndmask_b32_dpp v198, v126, v122, vcc quad_perm:[0,0,2,2] row_mask:0xf bank_mask:0xf
	v_cndmask_b32_dpp v199, v127, v123, vcc quad_perm:[0,0,2,2] row_mask:0xf bank_mask:0xf
	s_not_b64 vcc, vcc
	v_cndmask_b32_dpp v108, v104, v108, vcc quad_perm:[1,1,3,3] row_mask:0xf bank_mask:0xf
	v_cndmask_b32_dpp v109, v105, v109, vcc quad_perm:[1,1,3,3] row_mask:0xf bank_mask:0xf
	v_cndmask_b32_dpp v110, v106, v110, vcc quad_perm:[1,1,3,3] row_mask:0xf bank_mask:0xf
	v_cndmask_b32_dpp v111, v107, v111, vcc quad_perm:[1,1,3,3] row_mask:0xf bank_mask:0xf
	v_cndmask_b32_dpp v124, v120, v124, vcc quad_perm:[1,1,3,3] row_mask:0xf bank_mask:0xf
	v_cndmask_b32_dpp v125, v121, v125, vcc quad_perm:[1,1,3,3] row_mask:0xf bank_mask:0xf
	v_cndmask_b32_dpp v126, v122, v126, vcc quad_perm:[1,1,3,3] row_mask:0xf bank_mask:0xf
	v_cndmask_b32_dpp v127, v123, v127, vcc quad_perm:[1,1,3,3] row_mask:0xf bank_mask:0xf
	s_not_b64 vcc, vcc
	global_store_dwordx4 v[158:159], v[192:195], off nt
	global_store_dwordx4 v[158:159], v[196:199], off offset:512 nt
	global_store_dwordx4 v[160:161], v[108:111], off nt
	global_store_dwordx4 v[160:161], v[124:127], off offset:512 nt
	s_andn2_b64 vcc, exec, s[0:1]
	s_mov_b64 s[0:1], -1
	s_cbranch_vccnz .LBB0_474
	v_lshl_add_u32 v0, s34, 8, v140
	s_lshl_b64 s[0:1], s[46:47], 25
	v_lshl_or_b32 v2, s30, 8, v143
	s_add_u32 s0, s62, s0
	v_or_b32_e32 v12, 16, v0
	s_addc_u32 s1, s63, s1
	v_ashrrev_i32_e32 v3, 31, v2
	v_ashrrev_i32_e32 v1, 31, v0
	v_ashrrev_i32_e32 v13, 31, v12
	v_lshl_add_u64 v[4:5], v[2:3], 1, s[0:1]
	v_lshlrev_b64 v[2:3], 12, v[0:1]
	v_lshlrev_b64 v[12:13], 12, v[12:13]
	v_lshl_add_u64 v[16:17], v[4:5], 0, v[2:3]
	v_lshl_add_u64 v[18:19], v[4:5], 0, v[12:13]
	global_load_dwordx2 v[2:3], v[16:17], off
	global_load_dwordx2 v[6:7], v[16:17], off offset:32
	global_load_dwordx2 v[10:11], v[16:17], off offset:256
	global_load_dwordx2 v[8:9], v[16:17], off offset:288
	global_load_dwordx2 v[12:13], v[18:19], off
	global_load_dwordx2 v[14:15], v[18:19], off offset:32
	global_load_dwordx2 v[26:27], v[18:19], off offset:256
	global_load_dwordx2 v[24:25], v[18:19], off offset:288
	v_or_b32_e32 v18, 32, v0
	v_or_b32_e32 v0, 48, v0
	v_ashrrev_i32_e32 v19, 31, v18
	v_ashrrev_i32_e32 v1, 31, v0
	v_lshlrev_b64 v[18:19], 12, v[18:19]
	v_lshlrev_b64 v[0:1], 12, v[0:1]
	v_lshl_add_u64 v[18:19], v[4:5], 0, v[18:19]
	v_lshl_add_u64 v[0:1], v[4:5], 0, v[0:1]
	v_add_co_u32_e32 v4, vcc, s53, v16
	global_load_dwordx2 v[28:29], v[18:19], off
	global_load_dwordx2 v[30:31], v[18:19], off offset:32
	global_load_dwordx2 v[42:43], v[18:19], off offset:256
	global_load_dwordx2 v[40:41], v[18:19], off offset:288
	v_addc_co_u32_e32 v5, vcc, 0, v17, vcc
	global_load_dwordx2 v[44:45], v[0:1], off
	global_load_dwordx2 v[46:47], v[0:1], off offset:32
	global_load_dwordx2 v[58:59], v[0:1], off offset:256
	global_load_dwordx2 v[62:63], v[0:1], off offset:288
	v_lshl_add_u64 v[0:1], v[16:17], 0, s[4:5]
	global_load_dwordx2 v[66:67], v[4:5], off
	global_load_dwordx2 v[70:71], v[0:1], off offset:32
	global_load_dwordx2 v[76:77], v[0:1], off offset:256
	global_load_dwordx2 v[72:73], v[0:1], off offset:288
	v_add_co_u32_e32 v4, vcc, s54, v16
	v_lshl_add_u64 v[0:1], v[16:17], 0, s[6:7]
	s_nop 0
	v_addc_co_u32_e32 v5, vcc, 0, v17, vcc
	global_load_dwordx2 v[74:75], v[4:5], off
	global_load_dwordx2 v[78:79], v[0:1], off offset:32
	global_load_dwordx2 v[90:91], v[0:1], off offset:256
	global_load_dwordx2 v[88:89], v[0:1], off offset:288
	v_add_co_u32_e32 v4, vcc, s55, v16
	v_lshl_add_u64 v[0:1], v[16:17], 0, s[8:9]
	s_nop 0
	v_addc_co_u32_e32 v5, vcc, 0, v17, vcc
	global_load_dwordx2 v[100:101], v[4:5], off
	global_load_dwordx2 v[102:103], v[0:1], off offset:32
	global_load_dwordx2 v[106:107], v[0:1], off offset:256
	global_load_dwordx2 v[104:105], v[0:1], off offset:288
	v_add_co_u32_e32 v4, vcc, 0xb0000, v16
	v_lshl_add_u64 v[0:1], v[16:17], 0, s[10:11]
	s_nop 0
	v_addc_co_u32_e32 v5, vcc, 0, v17, vcc
	global_load_dwordx2 v[108:109], v[4:5], off
	global_load_dwordx2 v[110:111], v[0:1], off offset:32
	global_load_dwordx2 v[122:123], v[0:1], off offset:256
	global_load_dwordx2 v[126:127], v[0:1], off offset:288
	s_andn2_b64 vcc, exec, s[12:13]
	s_cbranch_vccnz .LBB0_473
	s_barrier
	s_branch .LBB0_473

	.amdhsa_kernel _Z14fwd_megakernel4Args
		.amdhsa_group_segment_fixed_size 147456
		.amdhsa_private_segment_fixed_size 0
		.amdhsa_kernarg_size 400
		.amdhsa_user_sgpr_count 2
		.amdhsa_user_sgpr_dispatch_ptr 0
		.amdhsa_user_sgpr_queue_ptr 0
		.amdhsa_user_sgpr_kernarg_segment_ptr 1
		.amdhsa_user_sgpr_dispatch_id 0
		.amdhsa_user_sgpr_kernarg_preload_length 0
		.amdhsa_user_sgpr_kernarg_preload_offset 0
		.amdhsa_user_sgpr_private_segment_size 0
		.amdhsa_uses_dynamic_stack 0
		.amdhsa_enable_private_segment 0
		.amdhsa_system_sgpr_workgroup_id_x 1
		.amdhsa_system_sgpr_workgroup_id_y 0
		.amdhsa_system_sgpr_workgroup_id_z 0
		.amdhsa_system_sgpr_workgroup_info 0
		.amdhsa_system_vgpr_workitem_id 2
		.amdhsa_next_free_vgpr 252
		.amdhsa_next_free_sgpr 102
		.amdhsa_accum_offset 252
		.amdhsa_reserve_vcc 1
		.amdhsa_float_round_mode_32 0
		.amdhsa_float_round_mode_16_64 0
		.amdhsa_float_denorm_mode_32 3
		.amdhsa_float_denorm_mode_16_64 3
		.amdhsa_dx10_clamp 1
		.amdhsa_ieee_mode 1
		.amdhsa_fp16_overflow 0
		.amdhsa_tg_split 0
		.amdhsa_exception_fp_ieee_invalid_op 0
		.amdhsa_exception_fp_denorm_src 0
		.amdhsa_exception_fp_ieee_div_zero 0
		.amdhsa_exception_fp_ieee_overflow 0
		.amdhsa_exception_fp_ieee_underflow 0
		.amdhsa_exception_fp_ieee_inexact 0
		.amdhsa_exception_int_div_zero 0
	.end_amdhsa_kernel

amdhsa.kernels:
  - .agpr_count:     0
    .args:
      - .offset:         0
        .size:           144
        .value_kind:     by_value
      - .offset:         144
        .size:           4
        .value_kind:     hidden_block_count_x
      - .offset:         148
        .size:           4
        .value_kind:     hidden_block_count_y
      - .offset:         152
        .size:           4
        .value_kind:     hidden_block_count_z
      - .offset:         156
        .size:           2
        .value_kind:     hidden_group_size_x
      - .offset:         158
        .size:           2
        .value_kind:     hidden_group_size_y
      - .offset:         160
        .size:           2
        .value_kind:     hidden_group_size_z
      - .offset:         162
        .size:           2
        .value_kind:     hidden_remainder_x
      - .offset:         164
        .size:           2
        .value_kind:     hidden_remainder_y
      - .offset:         166
        .size:           2
        .value_kind:     hidden_remainder_z
      - .offset:         184
        .size:           8
        .value_kind:     hidden_global_offset_x
      - .offset:         192
        .size:           8
        .value_kind:     hidden_global_offset_y
      - .offset:         200
        .size:           8
        .value_kind:     hidden_global_offset_z
      - .offset:         208
        .size:           2
        .value_kind:     hidden_grid_dims
      - .offset:         232
        .size:           8
        .value_kind:     hidden_multigrid_sync_arg
    .group_segment_fixed_size: 147456
    .kernarg_segment_align: 8
    .kernarg_segment_size: 400
    .language:       OpenCL C
    .language_version:
      - 2
      - 0
    .max_flat_workgroup_size: 512
    .name:           _Z14fwd_megakernel4Args
    .private_segment_fixed_size: 0
    .sgpr_count:     108
    .sgpr_spill_count: 2
    .symbol:         _Z14fwd_megakernel4Args.kd
    .uniform_work_group_size: 1
    .uses_dynamic_stack: false
    .vgpr_count:     252
    .vgpr_spill_count: 0
    .wavefront_size: 64
